# instruction selection: compressed-branch pass-2 packed multiplies and per-tile horizontal packed adds as scalar ops
# speedup vs baseline: 1.0006x; 1.0006x over previous
.LBB0_812:
	v_exp_f32_e32 v2, v100
	v_exp_f32_e32 v3, v101
	v_exp_f32_e32 v100, v84
	v_exp_f32_e32 v101, v85
	v_exp_f32_e32 v102, v102
	v_exp_f32_e32 v103, v103
	v_exp_f32_e32 v178, v86
	v_exp_f32_e32 v179, v87
	v_add_f32_e32 v84, 0, v2
	v_add_f32_e32 v85, 0, v3
	v_exp_f32_e32 v104, v104
	v_exp_f32_e32 v105, v105
	v_add_f32_e32 v84, v100, v84
	v_add_f32_e32 v85, v101, v85
	v_exp_f32_e32 v204, v88
	v_exp_f32_e32 v205, v89
	v_add_f32_e32 v84, v102, v84
	v_add_f32_e32 v85, v103, v85
	v_exp_f32_e32 v106, v106
	v_exp_f32_e32 v107, v107
	v_add_f32_e32 v84, v178, v84
	v_add_f32_e32 v85, v179, v85
	v_exp_f32_e32 v206, v90
	v_exp_f32_e32 v207, v91
	v_add_f32_e32 v84, v104, v84
	v_add_f32_e32 v85, v105, v85
	v_exp_f32_e32 v90, v108
	v_exp_f32_e32 v91, v109
	v_add_f32_e32 v84, v204, v84
	v_add_f32_e32 v85, v205, v85
	v_exp_f32_e32 v108, v92
	v_exp_f32_e32 v109, v93
	v_add_f32_e32 v84, v106, v84
	v_add_f32_e32 v85, v107, v85
	v_exp_f32_e32 v92, v110
	v_exp_f32_e32 v93, v111
	v_add_f32_e32 v84, v206, v84
	v_add_f32_e32 v85, v207, v85
	v_exp_f32_e32 v110, v94
	v_exp_f32_e32 v111, v95
	v_add_f32_e32 v84, v90, v84
	v_add_f32_e32 v85, v91, v85
	v_exp_f32_e32 v94, v112
	v_exp_f32_e32 v95, v113
	v_add_f32_e32 v84, v108, v84
	v_add_f32_e32 v85, v109, v85
	v_exp_f32_e32 v112, v96
	v_exp_f32_e32 v113, v97
	v_add_f32_e32 v84, v92, v84
	v_add_f32_e32 v85, v93, v85
	v_exp_f32_e32 v96, v114
	v_exp_f32_e32 v97, v115
	v_add_f32_e32 v84, v110, v84
	v_add_f32_e32 v85, v111, v85
	v_exp_f32_e32 v114, v98
	v_add_f32_e32 v84, v94, v84
	v_add_f32_e32 v85, v95, v85
	v_exp_f32_e32 v115, v99
	v_add_f32_e32 v84, v112, v84
	v_add_f32_e32 v85, v113, v85
	v_cvt_pk_bf16_f32 v87, v102, v103
	v_add_f32_e32 v84, v96, v84
	v_add_f32_e32 v85, v97, v85
	v_cvt_pk_bf16_f32 v88, v104, v105
	v_cvt_pk_bf16_f32 v89, v106, v107
	v_cvt_pk_bf16_f32 v90, v90, v91
	v_cvt_pk_bf16_f32 v91, v92, v93
	v_cvt_pk_bf16_f32 v92, v94, v95
	v_cvt_pk_bf16_f32 v93, v96, v97
	v_cvt_pk_bf16_f32 v94, v100, v101
	v_cvt_pk_bf16_f32 v96, v204, v205
	v_cvt_pk_bf16_f32 v97, v206, v207
	v_cvt_pk_bf16_f32 v98, v108, v109
	v_cvt_pk_bf16_f32 v99, v110, v111
	v_cvt_pk_bf16_f32 v100, v112, v113
	ds_read_b128 v[102:105], v0 offset:9216
	ds_read_b128 v[106:109], v0 offset:9248
	ds_read_b128 v[110:113], v0 offset:9280
	ds_read_b128 v[204:207], v0 offset:9312
	v_add_f32_e32 v84, v114, v84
	v_add_f32_e32 v85, v115, v85
	v_cvt_pk_bf16_f32 v86, v2, v3
	v_add_f32_e32 v84, v84, v85
	v_mov_b32_e32 v85, v84
	v_cvt_pk_bf16_f32 v95, v178, v179
	v_mov_b32_e32 v85, v84
	s_nop 1
	v_permlane32_swap_b32_e32 v84, v85
	v_cvt_pk_bf16_f32 v101, v114, v115
	s_waitcnt lgkmcnt(3)
	v_mfma_f32_32x32x16_bf16 v[36:51], v[102:105], v[86:89], v[36:51]
	s_waitcnt lgkmcnt(2)
	v_mfma_f32_32x32x16_bf16 v[36:51], v[106:109], v[90:93], v[36:51]
	s_waitcnt lgkmcnt(1)
	v_mfma_f32_32x32x16_bf16 v[36:51], v[110:113], v[94:97], v[36:51]
	s_waitcnt lgkmcnt(0)
	v_mfma_f32_32x32x16_bf16 v[36:51], v[204:207], v[98:101], v[36:51]
	ds_read_b128 v[102:105], v0 offset:13824
	ds_read_b128 v[106:109], v0 offset:13856
	ds_read_b128 v[110:113], v0 offset:13888
	ds_read_b128 v[204:207], v0 offset:13920
	s_waitcnt lgkmcnt(3)
	v_mfma_f32_32x32x16_bf16 v[20:35], v[102:105], v[86:89], v[20:35]
	s_waitcnt lgkmcnt(2)
	v_mfma_f32_32x32x16_bf16 v[20:35], v[106:109], v[90:93], v[20:35]
	s_waitcnt lgkmcnt(1)
	v_mfma_f32_32x32x16_bf16 v[20:35], v[110:113], v[94:97], v[20:35]
	s_waitcnt lgkmcnt(0)
	v_mfma_f32_32x32x16_bf16 v[20:35], v[204:207], v[98:101], v[20:35]
	s_andn2_b64 vcc, exec, s[0:1]
	s_cbranch_vccnz .LBB0_788
	v_add3_u32 v0, s20, v171, v166
	s_waitcnt vmcnt(1)
	ds_write_b128 v0, v[140:143]
	s_waitcnt vmcnt(0)
	ds_write_b128 v0, v[144:147] offset:9216
	s_and_saveexec_b64 s[0:1], s[6:7]
	s_cbranch_execz .LBB0_787
	v_add_f32_e32 v167, v167, v222
	v_sub_f32_e32 v167, v155, v167
	v_cvt_pk_bf16_f32 v0, v167, 0
	v_and_b32_e32 v2, 0xffff, v0
	v_lshlrev_b32_e32 v0, 16, v0
	v_sub_f32_e32 v0, v167, v0
	v_cvt_pk_bf16_f32 v0, v0, 0
	v_lshl_or_b32 v0, v0, 16, v2
	v_mov_b32_e32 v2, v1
	v_mov_b32_e32 v3, v1
	v_add_u32_e32 v86, s20, v172
	ds_write_b128 v86, v[0:3] offset:128
	s_branch .LBB0_787

.LBB0_845:
	v_exp_f32_e32 v34, v34
	v_exp_f32_e32 v35, v35
	v_exp_f32_e32 v18, v18
	v_exp_f32_e32 v19, v19
	v_exp_f32_e32 v20, v20
	v_add_f32_e32 v34, 0, v34
	v_add_f32_e32 v35, 0, v35
	v_exp_f32_e32 v21, v21
	v_add_f32_e32 v18, v18, v34
	v_add_f32_e32 v19, v19, v35
	v_exp_f32_e32 v34, v36
	v_exp_f32_e32 v35, v37
	v_exp_f32_e32 v22, v22
	v_exp_f32_e32 v23, v23
	s_add_i32 s14, s19, 1
	v_add_f32_e32 v18, v34, v18
	v_add_f32_e32 v19, v35, v19
	s_cmp_lg_u32 s14, 3
	v_add_f32_e32 v18, v20, v18
	v_add_f32_e32 v19, v21, v19
	v_exp_f32_e32 v20, v38
	v_exp_f32_e32 v21, v39
	s_cselect_b32 s24, s14, 0
	s_add_i32 s14, s24, 1
	s_cmp_lg_u32 s14, 3
	v_add_f32_e32 v18, v20, v18
	v_add_f32_e32 v19, v21, v19
	v_exp_f32_e32 v20, v40
	v_exp_f32_e32 v21, v41
	v_add_f32_e32 v18, v22, v18
	v_add_f32_e32 v19, v23, v19
	v_exp_f32_e32 v22, v24
	v_exp_f32_e32 v23, v25
	v_add_f32_e32 v18, v20, v18
	v_add_f32_e32 v19, v21, v19
	v_exp_f32_e32 v20, v42
	v_exp_f32_e32 v21, v43
	v_add_f32_e32 v18, v22, v18
	v_add_f32_e32 v19, v23, v19
	v_exp_f32_e32 v22, v26
	v_exp_f32_e32 v23, v27
	v_add_f32_e32 v18, v20, v18
	v_add_f32_e32 v19, v21, v19
	v_exp_f32_e32 v20, v44
	v_exp_f32_e32 v21, v45
	v_add_f32_e32 v18, v22, v18
	v_add_f32_e32 v19, v23, v19
	v_exp_f32_e32 v22, v28
	v_exp_f32_e32 v23, v29
	v_add_f32_e32 v18, v20, v18
	v_add_f32_e32 v19, v21, v19
	v_exp_f32_e32 v20, v46
	v_exp_f32_e32 v21, v47
	v_add_f32_e32 v18, v22, v18
	v_add_f32_e32 v19, v23, v19
	v_exp_f32_e32 v22, v30
	v_exp_f32_e32 v23, v31
	v_add_f32_e32 v18, v20, v18
	v_add_f32_e32 v19, v21, v19
	v_exp_f32_e32 v20, v48
	v_exp_f32_e32 v21, v49
	v_add_f32_e32 v18, v22, v18
	v_add_f32_e32 v19, v23, v19
	v_exp_f32_e32 v22, v32
	v_exp_f32_e32 v23, v33
	v_add_f32_e32 v18, v20, v18
	v_add_f32_e32 v19, v21, v19
	s_cselect_b32 s19, s14, 0
	s_add_i32 s23, s20, -2
	v_add_f32_e32 v18, v22, v18
	v_add_f32_e32 v19, v23, v19
	s_cmp_ge_i32 s23, s17
	v_add_f32_e32 v18, v18, v19
	v_mov_b32_e32 v19, v18
	s_nop 0
	v_mov_b32_e32 v0, v18
	s_nop 1
	v_permlane32_swap_b32_e32 v18, v0
	s_cbranch_scc1 .LBB0_847
	s_mul_i32 s14, s19, 0x4900
	v_add_u32_e32 v19, s14, v101
	s_waitcnt vmcnt(0)
	ds_write_b128 v19, v[50:53]

.LBB0_854:
	v_exp_f32_e32 v34, v34
	v_exp_f32_e32 v35, v35
	v_exp_f32_e32 v18, v18
	v_exp_f32_e32 v19, v19
	v_exp_f32_e32 v20, v20
	v_add_f32_e32 v34, 0, v34
	v_add_f32_e32 v35, 0, v35
	v_exp_f32_e32 v21, v21
	v_add_f32_e32 v18, v18, v34
	v_add_f32_e32 v19, v19, v35
	v_exp_f32_e32 v34, v36
	v_exp_f32_e32 v35, v37
	v_exp_f32_e32 v22, v22
	v_exp_f32_e32 v23, v23
	s_andn2_b64 vcc, exec, s[12:13]
	v_add_f32_e32 v18, v34, v18
	v_add_f32_e32 v19, v35, v19
	s_nop 0
	v_add_f32_e32 v18, v20, v18
	v_add_f32_e32 v19, v21, v19
	v_exp_f32_e32 v20, v38
	v_exp_f32_e32 v21, v39
	s_nop 0
	v_add_f32_e32 v18, v20, v18
	v_add_f32_e32 v19, v21, v19
	v_exp_f32_e32 v20, v40
	v_exp_f32_e32 v21, v41
	v_add_f32_e32 v18, v22, v18
	v_add_f32_e32 v19, v23, v19
	v_exp_f32_e32 v22, v24
	v_exp_f32_e32 v23, v25
	v_add_f32_e32 v18, v20, v18
	v_add_f32_e32 v19, v21, v19
	v_exp_f32_e32 v20, v42
	v_exp_f32_e32 v21, v43
	v_add_f32_e32 v18, v22, v18
	v_add_f32_e32 v19, v23, v19
	v_exp_f32_e32 v22, v26
	v_exp_f32_e32 v23, v27
	v_add_f32_e32 v18, v20, v18
	v_add_f32_e32 v19, v21, v19
	v_exp_f32_e32 v20, v44
	v_exp_f32_e32 v21, v45
	v_add_f32_e32 v18, v22, v18
	v_add_f32_e32 v19, v23, v19
	v_exp_f32_e32 v22, v28
	v_exp_f32_e32 v23, v29
	v_add_f32_e32 v18, v20, v18
	v_add_f32_e32 v19, v21, v19
	v_exp_f32_e32 v20, v46
	v_exp_f32_e32 v21, v47
	v_add_f32_e32 v18, v22, v18
	v_add_f32_e32 v19, v23, v19
	v_exp_f32_e32 v22, v30
	v_exp_f32_e32 v23, v31
	v_add_f32_e32 v18, v20, v18
	v_add_f32_e32 v19, v21, v19
	v_exp_f32_e32 v20, v48
	v_exp_f32_e32 v21, v49
	v_add_f32_e32 v18, v22, v18
	v_add_f32_e32 v19, v23, v19
	v_exp_f32_e32 v22, v32
	v_exp_f32_e32 v23, v33
	v_add_f32_e32 v18, v20, v18
	v_add_f32_e32 v19, v21, v19
	s_nop 0
	v_add_f32_e32 v18, v22, v18
	v_add_f32_e32 v19, v23, v19
	s_nop 0
	v_add_f32_e32 v18, v18, v19
	v_mov_b32_e32 v19, v18
	s_nop 0
	v_mov_b32_e32 v0, v18
	s_nop 1
	v_permlane32_swap_b32_e32 v18, v0
	s_cbranch_vccnz .LBB0_838
	v_add3_u32 v19, s22, v207, v102
	s_waitcnt vmcnt(0)
	ds_write_b128 v19, v[54:57]
	s_branch .LBB0_838

.LBB0_866:
	s_nop 6
	v_exp_f32_e32 v66, v66
	v_exp_f32_e32 v67, v67
	v_exp_f32_e32 v68, v68
	v_exp_f32_e32 v69, v69
	v_exp_f32_e32 v70, v70
	v_mul_f32_e32 v66, v120, v66
	v_mul_f32_e32 v67, v121, v67
	v_exp_f32_e32 v71, v71
	v_mul_f32_e32 v68, v120, v68
	v_mul_f32_e32 v69, v121, v69
	v_add_f32_e32 v124, v66, v67
	v_fma_f32 v126, 0.5, v69, v68
	v_exp_f32_e32 v72, v72
	v_exp_f32_e32 v73, v73
	v_add_f32_e32 v124, v124, v126
	v_mul_f32_e32 v125, 0.5, v69
	v_mul_f32_e32 v70, v120, v70
	v_mul_f32_e32 v71, v121, v71
	v_add_f32_dpp v124, v124, v124 quad_perm:[1,0,3,2] row_mask:0xf bank_mask:0xf bound_ctrl:1
	v_mul_f32_e32 v72, v120, v72
	v_mul_f32_e32 v73, v121, v73
	v_exp_f32_e32 v74, v74
	v_add_f32_dpp v158, v124, v124 quad_perm:[2,3,0,1] row_mask:0xf bank_mask:0xf bound_ctrl:1
	v_mov_b32_e32 v124, 0
	v_fma_f32 v126, 0.5, v73, v72
	v_exp_f32_e32 v75, v75
	v_mov_b32_dpp v124, v125 quad_perm:[1,0,3,2] row_mask:0xf bank_mask:0xf
	v_fmac_f32_e32 v124, 0.5, v69
	v_exp_f32_e32 v76, v76
	v_exp_f32_e32 v77, v77
	v_add_f32_dpp v159, v124, v124 quad_perm:[2,3,0,1] row_mask:0xf bank_mask:0xf bound_ctrl:1
	v_add_f32_e32 v124, v70, v71
	v_add_f32_e32 v124, v124, v126
	v_mul_f32_e32 v125, 0.5, v73
	v_mul_f32_e32 v74, v120, v74
	v_mul_f32_e32 v75, v121, v75
	v_add_f32_dpp v124, v124, v124 quad_perm:[1,0,3,2] row_mask:0xf bank_mask:0xf bound_ctrl:1
	v_mul_f32_e32 v76, v120, v76
	v_mul_f32_e32 v77, v121, v77
	v_exp_f32_e32 v78, v78
	v_add_f32_dpp v170, v124, v124 quad_perm:[2,3,0,1] row_mask:0xf bank_mask:0xf bound_ctrl:1
	v_mov_b32_e32 v124, 0
	v_fma_f32 v126, 0.5, v77, v76
	v_exp_f32_e32 v79, v79
	v_mov_b32_dpp v124, v125 quad_perm:[1,0,3,2] row_mask:0xf bank_mask:0xf
	v_fmac_f32_e32 v124, 0.5, v73
	v_exp_f32_e32 v80, v80
	v_exp_f32_e32 v81, v81
	v_add_f32_dpp v171, v124, v124 quad_perm:[2,3,0,1] row_mask:0xf bank_mask:0xf bound_ctrl:1
	v_add_f32_e32 v124, v74, v75
	v_add_f32_e32 v124, v124, v126
	v_mul_f32_e32 v125, 0.5, v77
	v_mul_f32_e32 v78, v120, v78
	v_mul_f32_e32 v79, v121, v79
	v_add_f32_dpp v124, v124, v124 quad_perm:[1,0,3,2] row_mask:0xf bank_mask:0xf bound_ctrl:1
	v_mul_f32_e32 v80, v120, v80
	v_mul_f32_e32 v81, v121, v81
	v_exp_f32_e32 v50, v50
	v_add_f32_dpp v156, v124, v124 quad_perm:[2,3,0,1] row_mask:0xf bank_mask:0xf bound_ctrl:1
	v_mov_b32_e32 v124, 0
	v_fma_f32 v126, 0.5, v81, v80
	v_exp_f32_e32 v51, v51
	v_mov_b32_dpp v124, v125 quad_perm:[1,0,3,2] row_mask:0xf bank_mask:0xf
	v_fmac_f32_e32 v124, 0.5, v77
	v_exp_f32_e32 v52, v52
	v_exp_f32_e32 v53, v53
	v_add_f32_dpp v157, v124, v124 quad_perm:[2,3,0,1] row_mask:0xf bank_mask:0xf bound_ctrl:1
	v_add_f32_e32 v124, v78, v79
	v_add_f32_e32 v124, v124, v126
	v_mul_f32_e32 v125, 0.5, v81
	v_mul_f32_e32 v50, v120, v50
	v_mul_f32_e32 v51, v121, v51
	v_add_f32_dpp v124, v124, v124 quad_perm:[1,0,3,2] row_mask:0xf bank_mask:0xf bound_ctrl:1
	v_mul_f32_e32 v52, v120, v52
	v_mul_f32_e32 v53, v121, v53
	v_exp_f32_e32 v54, v54
	v_add_f32_dpp v152, v124, v124 quad_perm:[2,3,0,1] row_mask:0xf bank_mask:0xf bound_ctrl:1
	v_mov_b32_e32 v124, 0
	v_fma_f32 v126, 0.5, v53, v52
	v_exp_f32_e32 v55, v55
	v_mov_b32_dpp v124, v125 quad_perm:[1,0,3,2] row_mask:0xf bank_mask:0xf
	v_fmac_f32_e32 v124, 0.5, v81
	v_exp_f32_e32 v56, v56
	v_exp_f32_e32 v57, v57
	v_add_f32_dpp v153, v124, v124 quad_perm:[2,3,0,1] row_mask:0xf bank_mask:0xf bound_ctrl:1
	v_add_f32_e32 v124, v50, v51
	v_add_f32_e32 v124, v124, v126
	v_mul_f32_e32 v125, 0.5, v53
	v_mul_f32_e32 v54, v120, v54
	v_mul_f32_e32 v55, v121, v55
	v_add_f32_dpp v124, v124, v124 quad_perm:[1,0,3,2] row_mask:0xf bank_mask:0xf bound_ctrl:1
	v_mul_f32_e32 v56, v120, v56
	v_mul_f32_e32 v57, v121, v57
	v_exp_f32_e32 v58, v58
	v_add_f32_dpp v146, v124, v124 quad_perm:[2,3,0,1] row_mask:0xf bank_mask:0xf bound_ctrl:1
	v_mov_b32_e32 v124, 0
	v_fma_f32 v126, 0.5, v57, v56
	v_exp_f32_e32 v59, v59
	v_mov_b32_dpp v124, v125 quad_perm:[1,0,3,2] row_mask:0xf bank_mask:0xf
	v_fmac_f32_e32 v124, 0.5, v53
	v_exp_f32_e32 v60, v60
	v_exp_f32_e32 v61, v61
	v_add_f32_dpp v147, v124, v124 quad_perm:[2,3,0,1] row_mask:0xf bank_mask:0xf bound_ctrl:1
	v_add_f32_e32 v124, v54, v55
	v_add_f32_e32 v124, v124, v126
	v_mul_f32_e32 v125, 0.5, v57
	v_mul_f32_e32 v58, v120, v58
	v_mul_f32_e32 v59, v121, v59
	v_add_f32_dpp v124, v124, v124 quad_perm:[1,0,3,2] row_mask:0xf bank_mask:0xf bound_ctrl:1
	v_mul_f32_e32 v60, v120, v60
	v_mul_f32_e32 v61, v121, v61
	v_exp_f32_e32 v62, v62
	v_add_f32_dpp v144, v124, v124 quad_perm:[2,3,0,1] row_mask:0xf bank_mask:0xf bound_ctrl:1
	v_mov_b32_e32 v124, 0
	v_fma_f32 v126, 0.5, v61, v60
	v_exp_f32_e32 v63, v63
	v_mov_b32_dpp v124, v125 quad_perm:[1,0,3,2] row_mask:0xf bank_mask:0xf
	v_fmac_f32_e32 v124, 0.5, v57
	v_exp_f32_e32 v64, v64
	v_exp_f32_e32 v65, v65
	v_add_f32_dpp v145, v124, v124 quad_perm:[2,3,0,1] row_mask:0xf bank_mask:0xf bound_ctrl:1
	v_add_f32_e32 v124, v58, v59
	v_add_f32_e32 v124, v124, v126
	v_mul_f32_e32 v125, 0.5, v61
	v_mul_f32_e32 v62, v120, v62
	v_mul_f32_e32 v63, v121, v63
	v_add_f32_dpp v124, v124, v124 quad_perm:[1,0,3,2] row_mask:0xf bank_mask:0xf bound_ctrl:1
	v_mul_f32_e32 v64, v120, v64
	v_mul_f32_e32 v65, v121, v65
	v_mov_b32_e32 v219, v158
	v_add_f32_dpp v126, v124, v124 quad_perm:[2,3,0,1] row_mask:0xf bank_mask:0xf bound_ctrl:1
	v_mov_b32_e32 v124, 0
	v_fma_f32 v148, 0.5, v65, v64
	v_mov_b32_e32 v178, v159
	v_mov_b32_dpp v124, v125 quad_perm:[1,0,3,2] row_mask:0xf bank_mask:0xf
	v_fmac_f32_e32 v124, 0.5, v61
	v_mul_f32_e32 v125, 0.5, v65
	v_mov_b32_e32 v179, v170
	v_add_f32_dpp v127, v124, v124 quad_perm:[2,3,0,1] row_mask:0xf bank_mask:0xf bound_ctrl:1
	v_add_f32_e32 v124, v62, v63
	v_add_f32_e32 v124, v124, v148
	v_mov_b32_e32 v148, 0
	v_mov_b32_e32 v176, v171
	v_add_f32_dpp v124, v124, v124 quad_perm:[1,0,3,2] row_mask:0xf bank_mask:0xf bound_ctrl:1
	v_mov_b32_dpp v148, v125 quad_perm:[1,0,3,2] row_mask:0xf bank_mask:0xf
	v_fmac_f32_e32 v148, 0.5, v65
	v_add_f32_dpp v124, v124, v124 quad_perm:[2,3,0,1] row_mask:0xf bank_mask:0xf bound_ctrl:1
	v_mov_b32_e32 v177, v156
	v_add_f32_dpp v125, v148, v148 quad_perm:[2,3,0,1] row_mask:0xf bank_mask:0xf bound_ctrl:1
	v_mov_b32_e32 v174, v157
	v_mov_b32_e32 v175, v152
	v_mov_b32_e32 v172, v153
	v_mov_b32_e32 v173, v146
	v_mov_b32_e32 v154, v147
	v_mov_b32_e32 v155, v144
	v_mov_b32_e32 v150, v145
	v_mov_b32_e32 v151, v126
	v_mov_b32_e32 v148, v127
	v_mov_b32_e32 v149, v124
	v_mov_b32_e32 v218, v125
	v_permlane32_swap_b32_e32 v158, v219
	v_permlane32_swap_b32_e32 v159, v178
	v_permlane32_swap_b32_e32 v170, v179
	v_permlane32_swap_b32_e32 v171, v176
	v_permlane32_swap_b32_e32 v156, v177
	v_permlane32_swap_b32_e32 v157, v174
	v_permlane32_swap_b32_e32 v152, v175
	v_permlane32_swap_b32_e32 v153, v172
	v_permlane32_swap_b32_e32 v146, v173
	v_permlane32_swap_b32_e32 v147, v154
	v_permlane32_swap_b32_e32 v144, v155
	v_permlane32_swap_b32_e32 v145, v150
	v_permlane32_swap_b32_e32 v126, v151
	v_permlane32_swap_b32_e32 v127, v148
	v_permlane32_swap_b32_e32 v124, v149
	v_permlane32_swap_b32_e32 v125, v218
	s_and_saveexec_b64 s[10:11], s[6:7]
	s_cbranch_execz .LBB0_868
	ds_read2_b32 v[220:221], v0 offset1:1
	v_add_f32_e32 v159, v219, v159
	v_add_f32_e32 v156, v176, v156
	v_add_f32_e32 v157, v177, v157
	v_add_f32_e32 v152, v174, v152
	v_add_f32_e32 v153, v175, v153
	v_add_f32_e32 v146, v172, v146
	v_add_f32_e32 v147, v173, v147
	s_waitcnt lgkmcnt(0)
	v_add_f32_e32 v158, v220, v158
	v_add_f32_e32 v159, v221, v159
	ds_write2_b32 v0, v158, v159 offset1:1
	v_add_f32_e32 v158, v178, v170
	v_add_f32_e32 v159, v179, v171
	ds_read2_b32 v[170:171], v0 offset0:2 offset1:3
	v_add_f32_e32 v144, v154, v144
	v_add_f32_e32 v145, v155, v145
	v_add_f32_e32 v126, v150, v126
	v_add_f32_e32 v127, v151, v127
	v_add_f32_e32 v124, v148, v124
	v_add_f32_e32 v125, v149, v125
	s_waitcnt lgkmcnt(0)
	v_add_f32_e32 v158, v158, v170
	v_add_f32_e32 v159, v159, v171
	ds_write2_b32 v0, v158, v159 offset0:2 offset1:3
	ds_read2_b32 v[158:159], v0 offset0:4 offset1:5
	s_waitcnt lgkmcnt(0)
	v_add_f32_e32 v156, v156, v158
	v_add_f32_e32 v157, v157, v159
	ds_write2_b32 v0, v156, v157 offset0:4 offset1:5
	ds_read2_b32 v[156:157], v0 offset0:6 offset1:7
	s_waitcnt lgkmcnt(0)
	v_add_f32_e32 v152, v152, v156
	v_add_f32_e32 v153, v153, v157
	ds_write2_b32 v0, v152, v153 offset0:6 offset1:7
	ds_read2_b32 v[152:153], v0 offset0:8 offset1:9
	s_waitcnt lgkmcnt(0)
	v_add_f32_e32 v146, v146, v152
	v_add_f32_e32 v147, v147, v153
	ds_write2_b32 v0, v146, v147 offset0:8 offset1:9
	ds_read2_b32 v[146:147], v0 offset0:10 offset1:11
	s_waitcnt lgkmcnt(0)
	v_add_f32_e32 v144, v144, v146
	v_add_f32_e32 v145, v145, v147
	ds_write2_b32 v0, v144, v145 offset0:10 offset1:11
	ds_read2_b32 v[144:145], v0 offset0:12 offset1:13
	s_waitcnt lgkmcnt(0)
	v_add_f32_e32 v126, v126, v144
	v_add_f32_e32 v127, v127, v145
	ds_write2_b32 v0, v126, v127 offset0:12 offset1:13
	ds_read2_b32 v[126:127], v0 offset0:14 offset1:15
	s_waitcnt lgkmcnt(0)
	v_add_f32_e32 v124, v124, v126
	v_add_f32_e32 v125, v125, v127
	ds_write2_b32 v0, v124, v125 offset0:14 offset1:15
	ds_read_b32 v124, v0 offset:64
	s_waitcnt lgkmcnt(0)
	v_add_f32_e32 v124, v124, v218
	ds_write_b32 v0, v124 offset:64

.LBB0_875:
	s_nop 7
	v_exp_f32_e32 v18, v18
	v_exp_f32_e32 v19, v19
	v_exp_f32_e32 v20, v20
	v_exp_f32_e32 v21, v21
	v_exp_f32_e32 v22, v22
	v_mul_f32_e32 v18, v120, v18
	v_mul_f32_e32 v19, v121, v19
	v_exp_f32_e32 v23, v23
	v_mul_f32_e32 v20, v120, v20
	v_mul_f32_e32 v21, v121, v21
	v_add_f32_e32 v124, v18, v19
	v_fma_f32 v126, 0.5, v21, v20
	v_exp_f32_e32 v24, v24
	v_exp_f32_e32 v25, v25
	v_add_f32_e32 v124, v124, v126
	v_mul_f32_e32 v125, 0.5, v21
	v_mul_f32_e32 v22, v120, v22
	v_mul_f32_e32 v23, v121, v23
	v_add_f32_dpp v124, v124, v124 quad_perm:[1,0,3,2] row_mask:0xf bank_mask:0xf bound_ctrl:1
	v_mul_f32_e32 v24, v120, v24
	v_mul_f32_e32 v25, v121, v25
	v_exp_f32_e32 v26, v26
	v_add_f32_dpp v158, v124, v124 quad_perm:[2,3,0,1] row_mask:0xf bank_mask:0xf bound_ctrl:1
	v_mov_b32_e32 v124, 0
	v_fma_f32 v126, 0.5, v25, v24
	v_exp_f32_e32 v27, v27
	v_mov_b32_dpp v124, v125 quad_perm:[1,0,3,2] row_mask:0xf bank_mask:0xf
	v_fmac_f32_e32 v124, 0.5, v21
	v_exp_f32_e32 v28, v28
	v_exp_f32_e32 v29, v29
	v_add_f32_dpp v159, v124, v124 quad_perm:[2,3,0,1] row_mask:0xf bank_mask:0xf bound_ctrl:1
	v_add_f32_e32 v124, v22, v23
	v_add_f32_e32 v124, v124, v126
	v_mul_f32_e32 v125, 0.5, v25
	v_mul_f32_e32 v26, v120, v26
	v_mul_f32_e32 v27, v121, v27
	v_add_f32_dpp v124, v124, v124 quad_perm:[1,0,3,2] row_mask:0xf bank_mask:0xf bound_ctrl:1
	v_mul_f32_e32 v28, v120, v28
	v_mul_f32_e32 v29, v121, v29
	v_exp_f32_e32 v30, v30
	v_add_f32_dpp v170, v124, v124 quad_perm:[2,3,0,1] row_mask:0xf bank_mask:0xf bound_ctrl:1
	v_mov_b32_e32 v124, 0
	v_fma_f32 v126, 0.5, v29, v28
	v_exp_f32_e32 v31, v31
	v_mov_b32_dpp v124, v125 quad_perm:[1,0,3,2] row_mask:0xf bank_mask:0xf
	v_fmac_f32_e32 v124, 0.5, v25
	v_exp_f32_e32 v32, v32
	v_exp_f32_e32 v33, v33
	v_add_f32_dpp v171, v124, v124 quad_perm:[2,3,0,1] row_mask:0xf bank_mask:0xf bound_ctrl:1
	v_add_f32_e32 v124, v26, v27
	v_add_f32_e32 v124, v124, v126
	v_mul_f32_e32 v125, 0.5, v29
	v_mul_f32_e32 v30, v120, v30
	v_mul_f32_e32 v31, v121, v31
	v_add_f32_dpp v124, v124, v124 quad_perm:[1,0,3,2] row_mask:0xf bank_mask:0xf bound_ctrl:1
	v_mul_f32_e32 v32, v120, v32
	v_mul_f32_e32 v33, v121, v33
	v_exp_f32_e32 v2, v2
	v_add_f32_dpp v156, v124, v124 quad_perm:[2,3,0,1] row_mask:0xf bank_mask:0xf bound_ctrl:1
	v_mov_b32_e32 v124, 0
	v_fma_f32 v126, 0.5, v33, v32
	v_exp_f32_e32 v3, v3
	v_mov_b32_dpp v124, v125 quad_perm:[1,0,3,2] row_mask:0xf bank_mask:0xf
	v_fmac_f32_e32 v124, 0.5, v29
	v_exp_f32_e32 v4, v4
	v_exp_f32_e32 v5, v5
	v_add_f32_dpp v157, v124, v124 quad_perm:[2,3,0,1] row_mask:0xf bank_mask:0xf bound_ctrl:1
	v_add_f32_e32 v124, v30, v31
	v_add_f32_e32 v124, v124, v126
	v_mul_f32_e32 v125, 0.5, v33
	v_mul_f32_e32 v2, v120, v2
	v_mul_f32_e32 v3, v121, v3
	v_add_f32_dpp v124, v124, v124 quad_perm:[1,0,3,2] row_mask:0xf bank_mask:0xf bound_ctrl:1
	v_mul_f32_e32 v4, v120, v4
	v_mul_f32_e32 v5, v121, v5
	v_exp_f32_e32 v6, v6
	v_add_f32_dpp v152, v124, v124 quad_perm:[2,3,0,1] row_mask:0xf bank_mask:0xf bound_ctrl:1
	v_mov_b32_e32 v124, 0
	v_fma_f32 v126, 0.5, v5, v4
	v_exp_f32_e32 v7, v7
	v_mov_b32_dpp v124, v125 quad_perm:[1,0,3,2] row_mask:0xf bank_mask:0xf
	v_fmac_f32_e32 v124, 0.5, v33
	v_exp_f32_e32 v8, v8
	v_exp_f32_e32 v9, v9
	v_add_f32_dpp v153, v124, v124 quad_perm:[2,3,0,1] row_mask:0xf bank_mask:0xf bound_ctrl:1
	v_add_f32_e32 v124, v2, v3
	v_add_f32_e32 v124, v124, v126
	v_mul_f32_e32 v125, 0.5, v5
	v_mul_f32_e32 v6, v120, v6
	v_mul_f32_e32 v7, v121, v7
	v_add_f32_dpp v124, v124, v124 quad_perm:[1,0,3,2] row_mask:0xf bank_mask:0xf bound_ctrl:1
	v_mul_f32_e32 v8, v120, v8
	v_mul_f32_e32 v9, v121, v9
	v_exp_f32_e32 v10, v10
	v_add_f32_dpp v146, v124, v124 quad_perm:[2,3,0,1] row_mask:0xf bank_mask:0xf bound_ctrl:1
	v_mov_b32_e32 v124, 0
	v_fma_f32 v126, 0.5, v9, v8
	v_exp_f32_e32 v11, v11
	v_mov_b32_dpp v124, v125 quad_perm:[1,0,3,2] row_mask:0xf bank_mask:0xf
	v_fmac_f32_e32 v124, 0.5, v5
	v_exp_f32_e32 v12, v12
	v_exp_f32_e32 v13, v13
	v_add_f32_dpp v147, v124, v124 quad_perm:[2,3,0,1] row_mask:0xf bank_mask:0xf bound_ctrl:1
	v_add_f32_e32 v124, v6, v7
	v_add_f32_e32 v124, v124, v126
	v_mul_f32_e32 v125, 0.5, v9
	v_mul_f32_e32 v10, v120, v10
	v_mul_f32_e32 v11, v121, v11
	v_add_f32_dpp v124, v124, v124 quad_perm:[1,0,3,2] row_mask:0xf bank_mask:0xf bound_ctrl:1
	v_mul_f32_e32 v12, v120, v12
	v_mul_f32_e32 v13, v121, v13
	v_exp_f32_e32 v14, v14
	v_add_f32_dpp v144, v124, v124 quad_perm:[2,3,0,1] row_mask:0xf bank_mask:0xf bound_ctrl:1
	v_mov_b32_e32 v124, 0
	v_fma_f32 v126, 0.5, v13, v12
	v_exp_f32_e32 v15, v15
	v_mov_b32_dpp v124, v125 quad_perm:[1,0,3,2] row_mask:0xf bank_mask:0xf
	v_fmac_f32_e32 v124, 0.5, v9
	v_exp_f32_e32 v16, v16
	v_exp_f32_e32 v17, v17
	v_add_f32_dpp v145, v124, v124 quad_perm:[2,3,0,1] row_mask:0xf bank_mask:0xf bound_ctrl:1
	v_add_f32_e32 v124, v10, v11
	v_add_f32_e32 v124, v124, v126
	v_mul_f32_e32 v125, 0.5, v13
	v_mul_f32_e32 v14, v120, v14
	v_mul_f32_e32 v15, v121, v15
	v_add_f32_dpp v124, v124, v124 quad_perm:[1,0,3,2] row_mask:0xf bank_mask:0xf bound_ctrl:1
	v_mul_f32_e32 v16, v120, v16
	v_mul_f32_e32 v17, v121, v17
	v_mov_b32_e32 v219, v158
	v_add_f32_dpp v126, v124, v124 quad_perm:[2,3,0,1] row_mask:0xf bank_mask:0xf bound_ctrl:1
	v_mov_b32_e32 v124, 0
	v_fma_f32 v148, 0.5, v17, v16
	v_mov_b32_e32 v178, v159
	v_mov_b32_dpp v124, v125 quad_perm:[1,0,3,2] row_mask:0xf bank_mask:0xf
	v_fmac_f32_e32 v124, 0.5, v13
	v_mul_f32_e32 v125, 0.5, v17
	v_mov_b32_e32 v179, v170
	v_add_f32_dpp v127, v124, v124 quad_perm:[2,3,0,1] row_mask:0xf bank_mask:0xf bound_ctrl:1
	v_add_f32_e32 v124, v14, v15
	v_add_f32_e32 v124, v124, v148
	v_mov_b32_e32 v148, 0
	v_mov_b32_e32 v176, v171
	v_add_f32_dpp v124, v124, v124 quad_perm:[1,0,3,2] row_mask:0xf bank_mask:0xf bound_ctrl:1
	v_mov_b32_dpp v148, v125 quad_perm:[1,0,3,2] row_mask:0xf bank_mask:0xf
	v_fmac_f32_e32 v148, 0.5, v17
	v_add_f32_dpp v124, v124, v124 quad_perm:[2,3,0,1] row_mask:0xf bank_mask:0xf bound_ctrl:1
	v_mov_b32_e32 v177, v156
	v_add_f32_dpp v125, v148, v148 quad_perm:[2,3,0,1] row_mask:0xf bank_mask:0xf bound_ctrl:1
	v_mov_b32_e32 v174, v157
	v_mov_b32_e32 v175, v152
	v_mov_b32_e32 v172, v153
	v_mov_b32_e32 v173, v146
	v_mov_b32_e32 v154, v147
	v_mov_b32_e32 v155, v144
	v_mov_b32_e32 v150, v145
	v_mov_b32_e32 v151, v126
	v_mov_b32_e32 v148, v127
	v_mov_b32_e32 v149, v124
	v_mov_b32_e32 v218, v125
	v_permlane32_swap_b32_e32 v158, v219
	v_permlane32_swap_b32_e32 v159, v178
	v_permlane32_swap_b32_e32 v170, v179
	v_permlane32_swap_b32_e32 v171, v176
	v_permlane32_swap_b32_e32 v156, v177
	v_permlane32_swap_b32_e32 v157, v174
	v_permlane32_swap_b32_e32 v152, v175
	v_permlane32_swap_b32_e32 v153, v172
	v_permlane32_swap_b32_e32 v146, v173
	v_permlane32_swap_b32_e32 v147, v154
	v_permlane32_swap_b32_e32 v144, v155
	v_permlane32_swap_b32_e32 v145, v150
	v_permlane32_swap_b32_e32 v126, v151
	v_permlane32_swap_b32_e32 v127, v148
	v_permlane32_swap_b32_e32 v124, v149
	v_permlane32_swap_b32_e32 v125, v218
	s_and_saveexec_b64 s[10:11], s[6:7]
	s_cbranch_execz .LBB0_877
	ds_read2_b32 v[220:221], v0 offset0:16 offset1:17
	v_add_f32_e32 v159, v219, v159
	v_add_f32_e32 v156, v176, v156
	v_add_f32_e32 v157, v177, v157
	v_add_f32_e32 v152, v174, v152
	v_add_f32_e32 v153, v175, v153
	v_add_f32_e32 v146, v172, v146
	v_add_f32_e32 v147, v173, v147
	s_waitcnt lgkmcnt(0)
	v_add_f32_e32 v158, v220, v158
	v_add_f32_e32 v159, v221, v159
	ds_write2_b32 v0, v158, v159 offset0:16 offset1:17
	v_add_f32_e32 v158, v178, v170
	v_add_f32_e32 v159, v179, v171
	ds_read2_b32 v[170:171], v0 offset0:18 offset1:19
	v_add_f32_e32 v144, v154, v144
	v_add_f32_e32 v145, v155, v145
	v_add_f32_e32 v126, v150, v126
	v_add_f32_e32 v127, v151, v127
	v_add_f32_e32 v124, v148, v124
	v_add_f32_e32 v125, v149, v125
	s_waitcnt lgkmcnt(0)
	v_add_f32_e32 v158, v158, v170
	v_add_f32_e32 v159, v159, v171
	ds_write2_b32 v0, v158, v159 offset0:18 offset1:19
	ds_read2_b32 v[158:159], v0 offset0:20 offset1:21
	s_waitcnt lgkmcnt(0)
	v_add_f32_e32 v156, v156, v158
	v_add_f32_e32 v157, v157, v159
	ds_write2_b32 v0, v156, v157 offset0:20 offset1:21
	ds_read2_b32 v[156:157], v0 offset0:22 offset1:23
	s_waitcnt lgkmcnt(0)
	v_add_f32_e32 v152, v152, v156
	v_add_f32_e32 v153, v153, v157
	ds_write2_b32 v0, v152, v153 offset0:22 offset1:23
	ds_read2_b32 v[152:153], v0 offset0:24 offset1:25
	s_waitcnt lgkmcnt(0)
	v_add_f32_e32 v146, v146, v152
	v_add_f32_e32 v147, v147, v153
	ds_write2_b32 v0, v146, v147 offset0:24 offset1:25
	ds_read2_b32 v[146:147], v0 offset0:26 offset1:27
	s_waitcnt lgkmcnt(0)
	v_add_f32_e32 v144, v144, v146
	v_add_f32_e32 v145, v145, v147
	ds_write2_b32 v0, v144, v145 offset0:26 offset1:27
	ds_read2_b32 v[144:145], v0 offset0:28 offset1:29
	s_waitcnt lgkmcnt(0)
	v_add_f32_e32 v126, v126, v144
	v_add_f32_e32 v127, v127, v145
	ds_write2_b32 v0, v126, v127 offset0:28 offset1:29
	ds_read2_b32 v[126:127], v0 offset0:30 offset1:31
	s_waitcnt lgkmcnt(0)
	v_add_f32_e32 v124, v124, v126
	v_add_f32_e32 v125, v125, v127
	ds_write2_b32 v0, v124, v125 offset0:30 offset1:31
	ds_read_b32 v124, v0 offset:128
	s_waitcnt lgkmcnt(0)
	v_add_f32_e32 v124, v124, v218
	ds_write_b32 v0, v124 offset:128

.LBB0_995:
	v_exp_f32_e32 v4, v80
	v_exp_f32_e32 v5, v81
	v_exp_f32_e32 v12, v64
	v_exp_f32_e32 v13, v65
	v_exp_f32_e32 v6, v82
	v_exp_f32_e32 v7, v83
	v_exp_f32_e32 v14, v66
	v_exp_f32_e32 v15, v67
	v_add_f32_e32 v2, 0, v4
	v_add_f32_e32 v3, 0, v5
	v_exp_f32_e32 v8, v84
	v_exp_f32_e32 v9, v85
	v_add_f32_e32 v2, v12, v2
	v_add_f32_e32 v3, v13, v3
	v_exp_f32_e32 v64, v68
	v_exp_f32_e32 v65, v69
	v_add_f32_e32 v2, v6, v2
	v_add_f32_e32 v3, v7, v3
	v_exp_f32_e32 v10, v86
	v_exp_f32_e32 v11, v87
	v_add_f32_e32 v2, v14, v2
	v_add_f32_e32 v3, v15, v3
	v_exp_f32_e32 v66, v70
	v_exp_f32_e32 v67, v71
	v_add_f32_e32 v2, v8, v2
	v_add_f32_e32 v3, v9, v3
	v_exp_f32_e32 v68, v88
	v_exp_f32_e32 v69, v89
	v_add_f32_e32 v2, v64, v2
	v_add_f32_e32 v3, v65, v3
	v_exp_f32_e32 v70, v72
	v_exp_f32_e32 v71, v73
	v_add_f32_e32 v2, v10, v2
	v_add_f32_e32 v3, v11, v3
	v_exp_f32_e32 v72, v90
	v_exp_f32_e32 v73, v91
	v_add_f32_e32 v2, v66, v2
	v_add_f32_e32 v3, v67, v3
	v_exp_f32_e32 v74, v74
	v_exp_f32_e32 v75, v75
	v_add_f32_e32 v2, v68, v2
	v_add_f32_e32 v3, v69, v3
	v_exp_f32_e32 v80, v92
	v_exp_f32_e32 v81, v93
	v_add_f32_e32 v2, v70, v2
	v_add_f32_e32 v3, v71, v3
	v_exp_f32_e32 v76, v76
	v_exp_f32_e32 v77, v77
	v_add_f32_e32 v2, v72, v2
	v_add_f32_e32 v3, v73, v3
	v_exp_f32_e32 v82, v94
	v_exp_f32_e32 v83, v95
	v_add_f32_e32 v2, v74, v2
	v_add_f32_e32 v3, v75, v3
	v_exp_f32_e32 v78, v78
	v_exp_f32_e32 v79, v79
	v_add_f32_e32 v2, v80, v2
	v_add_f32_e32 v3, v81, v3
	v_cvt_pk_bf16_f32 v4, v4, v5
	v_add_f32_e32 v2, v76, v2
	v_add_f32_e32 v3, v77, v3
	v_cvt_pk_bf16_f32 v5, v6, v7
	v_add_f32_e32 v2, v82, v2
	v_add_f32_e32 v3, v83, v3
	v_cvt_pk_bf16_f32 v6, v8, v9
	v_add_f32_e32 v2, v78, v2
	v_add_f32_e32 v3, v79, v3
	v_cvt_pk_bf16_f32 v8, v68, v69
	v_cvt_pk_bf16_f32 v9, v72, v73
	v_cvt_pk_bf16_f32 v12, v12, v13
	v_cvt_pk_bf16_f32 v13, v14, v15
	v_cvt_pk_bf16_f32 v14, v64, v65
	v_cvt_pk_bf16_f32 v15, v66, v67
	v_cvt_pk_bf16_f32 v98, v70, v71
	v_cvt_pk_bf16_f32 v99, v74, v75
	v_cvt_pk_bf16_f32 v100, v76, v77
	v_cvt_pk_bf16_f32 v101, v78, v79
	ds_read_b128 v[64:67], v0 offset:9216
	ds_read_b128 v[68:71], v0 offset:9248
	ds_read_b128 v[72:75], v0 offset:9280
	ds_read_b128 v[76:79], v0 offset:9312
	s_add_i32 s0, s9, 1
	s_cmp_lg_u32 s0, 3
	s_cselect_b32 s14, s0, 0
	s_add_i32 s0, s14, 1
	v_add_f32_e32 v2, v2, v3
	v_mov_b32_e32 v3, v2
	s_cmp_lg_u32 s0, 3
	v_mov_b32_e32 v3, v2
	s_cselect_b32 s9, s0, 0
	s_nop 0
	v_permlane32_swap_b32_e32 v2, v3
	v_cvt_pk_bf16_f32 v7, v10, v11
	v_cvt_pk_bf16_f32 v10, v80, v81
	v_cvt_pk_bf16_f32 v11, v82, v83
	s_waitcnt lgkmcnt(3)
	v_mfma_f32_32x32x16_bf16 v[16:31], v[64:67], v[4:7], v[16:31]
	s_waitcnt lgkmcnt(2)
	v_mfma_f32_32x32x16_bf16 v[16:31], v[68:71], v[8:11], v[16:31]
	s_waitcnt lgkmcnt(1)
	v_mfma_f32_32x32x16_bf16 v[16:31], v[72:75], v[12:15], v[16:31]
	s_waitcnt lgkmcnt(0)
	v_mfma_f32_32x32x16_bf16 v[80:95], v[76:79], v[98:101], v[16:31]
	s_nop 7
	ds_read_b128 v[16:19], v0 offset:13824
	ds_read_b128 v[20:23], v0 offset:13856
	ds_read_b128 v[24:27], v0 offset:13888
	ds_read_b128 v[28:31], v0 offset:13920
	s_waitcnt lgkmcnt(3)
	v_mfma_f32_32x32x16_bf16 v[48:63], v[16:19], v[4:7], v[48:63]
	s_waitcnt lgkmcnt(2)
	v_mfma_f32_32x32x16_bf16 v[48:63], v[20:23], v[8:11], v[48:63]
	s_waitcnt lgkmcnt(1)
	v_mfma_f32_32x32x16_bf16 v[48:63], v[24:27], v[12:15], v[48:63]
	s_waitcnt lgkmcnt(0)
	v_mfma_f32_32x32x16_bf16 v[64:79], v[28:31], v[98:101], v[48:63]
	s_add_i32 s12, s10, -2
	s_cmp_gt_i32 s12, s6
	s_cbranch_scc1 .LBB0_997
	s_mul_i32 s0, s9, 0x4900
	v_add_u32_e32 v0, s0, v171
	s_waitcnt vmcnt(1)
	ds_write_b128 v0, v[144:147]
	s_waitcnt vmcnt(0)
	ds_write_b128 v0, v[148:151] offset:9216

.LBB0_1005:
	v_exp_f32_e32 v6, v112
	v_exp_f32_e32 v7, v113
	v_exp_f32_e32 v14, v96
	v_exp_f32_e32 v15, v97
	v_exp_f32_e32 v8, v114
	v_exp_f32_e32 v9, v115
	v_exp_f32_e32 v98, v98
	v_exp_f32_e32 v99, v99
	v_add_f32_e32 v2, 0, v6
	v_add_f32_e32 v3, 0, v7
	v_exp_f32_e32 v10, v116
	v_exp_f32_e32 v11, v117
	v_add_f32_e32 v2, v14, v2
	v_add_f32_e32 v3, v15, v3
	v_exp_f32_e32 v100, v100
	v_exp_f32_e32 v101, v101
	v_add_f32_e32 v2, v8, v2
	v_add_f32_e32 v3, v9, v3
	v_exp_f32_e32 v12, v118
	v_exp_f32_e32 v13, v119
	v_add_f32_e32 v2, v98, v2
	v_add_f32_e32 v3, v99, v3
	v_exp_f32_e32 v102, v102
	v_exp_f32_e32 v103, v103
	v_add_f32_e32 v2, v10, v2
	v_add_f32_e32 v3, v11, v3
	v_exp_f32_e32 v96, v120
	v_exp_f32_e32 v97, v121
	v_add_f32_e32 v2, v100, v2
	v_add_f32_e32 v3, v101, v3
	v_exp_f32_e32 v104, v104
	v_exp_f32_e32 v105, v105
	v_add_f32_e32 v2, v12, v2
	v_add_f32_e32 v3, v13, v3
	v_exp_f32_e32 v112, v122
	v_exp_f32_e32 v113, v123
	v_add_f32_e32 v2, v102, v2
	v_add_f32_e32 v3, v103, v3
	v_exp_f32_e32 v106, v106
	v_exp_f32_e32 v107, v107
	v_add_f32_e32 v2, v96, v2
	v_add_f32_e32 v3, v97, v3
	v_exp_f32_e32 v114, v124
	v_exp_f32_e32 v115, v125
	v_add_f32_e32 v2, v104, v2
	v_add_f32_e32 v3, v105, v3
	v_exp_f32_e32 v108, v108
	v_exp_f32_e32 v109, v109
	v_add_f32_e32 v2, v112, v2
	v_add_f32_e32 v3, v113, v3
	v_exp_f32_e32 v116, v126
	v_exp_f32_e32 v117, v127
	v_add_f32_e32 v2, v106, v2
	v_add_f32_e32 v3, v107, v3
	v_exp_f32_e32 v110, v110
	v_exp_f32_e32 v111, v111
	v_add_f32_e32 v2, v114, v2
	v_add_f32_e32 v3, v115, v3
	v_cvt_pk_bf16_f32 v6, v6, v7
	v_add_f32_e32 v2, v108, v2
	v_add_f32_e32 v3, v109, v3
	v_cvt_pk_bf16_f32 v7, v8, v9
	v_add_f32_e32 v2, v116, v2
	v_add_f32_e32 v3, v117, v3
	v_cvt_pk_bf16_f32 v8, v10, v11
	v_add_f32_e32 v2, v110, v2
	v_add_f32_e32 v3, v111, v3
	v_cvt_pk_bf16_f32 v9, v12, v13
	v_cvt_pk_bf16_f32 v10, v96, v97
	v_cvt_pk_bf16_f32 v11, v112, v113
	v_cvt_pk_bf16_f32 v12, v114, v115
	v_cvt_pk_bf16_f32 v13, v116, v117
	v_cvt_pk_bf16_f32 v97, v98, v99
	v_cvt_pk_bf16_f32 v98, v100, v101
	v_cvt_pk_bf16_f32 v99, v102, v103
	v_cvt_pk_bf16_f32 v100, v104, v105
	v_cvt_pk_bf16_f32 v101, v106, v107
	v_cvt_pk_bf16_f32 v102, v108, v109
	v_cvt_pk_bf16_f32 v103, v110, v111
	ds_read_b128 v[104:107], v4 offset:9216
	ds_read_b128 v[108:111], v4 offset:9248
	ds_read_b128 v[112:115], v4 offset:9280
	ds_read_b128 v[116:119], v4 offset:9312
	v_add_f32_e32 v2, v2, v3
	v_mov_b32_e32 v3, v2
	v_cvt_pk_bf16_f32 v96, v14, v15
	v_mov_b32_e32 v3, v2
	s_nop 1
	v_permlane32_swap_b32_e32 v2, v3
	s_waitcnt lgkmcnt(3)
	v_mfma_f32_32x32x16_bf16 v[16:31], v[104:107], v[6:9], v[80:95]
	s_waitcnt lgkmcnt(2)
	v_mfma_f32_32x32x16_bf16 v[16:31], v[108:111], v[10:13], v[16:31]
	s_waitcnt lgkmcnt(1)
	v_mfma_f32_32x32x16_bf16 v[16:31], v[112:115], v[96:99], v[16:31]
	s_waitcnt lgkmcnt(0)
	v_mfma_f32_32x32x16_bf16 v[16:31], v[116:119], v[100:103], v[16:31]
	ds_read_b128 v[104:107], v4 offset:13824
	ds_read_b128 v[108:111], v4 offset:13856
	ds_read_b128 v[112:115], v4 offset:13888
	ds_read_b128 v[116:119], v4 offset:13920
	s_waitcnt lgkmcnt(3)
	v_mfma_f32_32x32x16_bf16 v[48:63], v[104:107], v[6:9], v[64:79]
	s_waitcnt lgkmcnt(2)
	v_mfma_f32_32x32x16_bf16 v[48:63], v[108:111], v[10:13], v[48:63]
	s_waitcnt lgkmcnt(1)
	v_mfma_f32_32x32x16_bf16 v[48:63], v[112:115], v[96:99], v[48:63]
	s_waitcnt lgkmcnt(0)
	v_mfma_f32_32x32x16_bf16 v[48:63], v[116:119], v[100:103], v[48:63]
	s_andn2_b64 vcc, exec, s[2:3]
	s_cbranch_vccnz .LBB0_1007
	v_add3_u32 v4, s11, v207, v170
	s_waitcnt vmcnt(1)
	ds_write_b128 v4, v[152:155]
	s_waitcnt vmcnt(0)
	ds_write_b128 v4, v[156:159] offset:9216
